# experiment: s_sleep 3 for waves 4-7 after each step barrier in retention loop (stagger)
# baseline (speedup 1.0000x reference)
.LBB0_1353:
	s_or_b64 exec, exec, s[0:1]
	s_add_i32 s3, s2, 0xc0
	s_add_i32 s16, s2, 0x180
	s_add_u32 s17, s24, 0x2d22800
	s_addc_u32 s19, s25, 0
	s_add_u32 s28, s22, 0x4800000
	s_addc_u32 s29, s23, 0
	s_mov_b32 s35, 0
	s_movk_i32 s48, 0x400
	s_mov_b32 s49, 0xbfb8aa3b
	s_mov_b32 s50, 0x800000
	s_mov_b32 s51, 0x3f317217
	s_mov_b32 s52, 0x7f800000
	s_mov_b32 s53, 0xbd22000
	v_mov_b32_e32 v2, 0
	s_movk_i32 s54, 0x110
	v_mov_b32_e32 v172, 0x41b17218
	s_waitcnt lgkmcnt(0)
	s_barrier
	v_readfirstlane_b32 s98, v224
	s_nop 0
	s_lshr_b32 s98, s98, 8
	s_branch .LBB0_1356

.LBB0_1370:
	s_add_i32 s1, s57, -1
	s_waitcnt vmcnt(7)
	ds_write_b128 v175, v[72:75]
	ds_write_b128 v175, v[68:71] offset:8704
	ds_write_b128 v175, v[64:67] offset:17408
	v_cndmask_b32_e32 v65, v180, v173, vcc
	v_xor_b32_e32 v66, 0xffffffef, v173
	v_xor_b32_e32 v70, 0xffffffcf, v173
	s_min_u32 s18, s1, s0
	v_add_u32_e32 v69, 48, v173
	v_xor_b32_e32 v67, 0xffffffdf, v173
	v_add_u32_e32 v71, s55, v66
	v_add_u32_e32 v66, s56, v65
	v_add_u32_e32 v70, s55, v70
	v_lshl_add_u32 v73, s18, 5, v174
	v_add_u32_e32 v64, 16, v173
	v_add_u32_e32 v68, 32, v173
	v_add_u32_e32 v65, s55, v67
	v_ashrrev_i32_e32 v67, 31, v66
	v_cndmask_b32_e32 v69, v70, v69, vcc
	v_xad_u32 v70, v73, -1, s55
	v_cndmask_b32_e32 v71, v71, v64, vcc
	v_cndmask_b32_e32 v68, v65, v68, vcc
	v_lshlrev_b64 v[64:65], 11, v[66:67]
	v_cndmask_b32_e32 v67, v70, v73, vcc
	s_min_u32 s42, s57, s0
	v_lshl_add_u64 v[242:243], v[170:171], 0, v[64:65]
	v_add_u32_e32 v64, s56, v67
	v_lshl_add_u32 v72, s42, 5, v174
	v_ashrrev_i32_e32 v65, 31, v64
	v_cvt_pk_bf16_f32 v60, v44, v45
	v_cvt_pk_bf16_f32 v61, v46, v47
	v_cvt_pk_bf16_f32 v62, v40, v41
	v_cvt_pk_bf16_f32 v63, v42, v43
	v_xad_u32 v74, v72, -1, s55
	v_lshlrev_b64 v[64:65], 13, v[64:65]
	v_cndmask_b32_e32 v66, v74, v72, vcc
	v_or_b32_e32 v64, v64, v181
	v_add_u32_e32 v238, s56, v68
	v_add_u32_e32 v240, s56, v69
	v_add_u32_e32 v244, s56, v66
	v_lshl_add_u64 v[66:67], s[36:37], 0, v[64:65]
	v_lshl_add_u64 v[68:69], s[38:39], 0, v[64:65]
	v_lshl_add_u64 v[64:65], s[40:41], 0, v[64:65]
	v_add_u32_e32 v0, 0x1000, v178
	v_add_u32_e32 v1, 0x2000, v179
	v_add_u32_e32 v182, 0x3000, v179
	v_add_u32_e32 v236, s56, v71
	global_load_dwordx4 v[72:75], v[66:67], off
	s_nop 0
	global_load_dwordx4 v[68:71], v[68:69], off
	s_nop 0
	global_load_dwordx4 v[64:67], v[64:65], off
	s_waitcnt lgkmcnt(0)
	s_barrier
	s_cselect_b32 s99, 1, 0
	s_cmp_eq_u32 s98, 0
	s_cbranch_scc1 .Lstg_skip1
	s_sleep 3
.Lstg_skip1:
	s_cmp_lg_u32 s99, 0
	ds_read_b64 v[188:189], v178
	ds_read_b64 v[190:191], v178 offset:32
	ds_read_b64 v[192:193], v0 offset:256
	ds_read_b64 v[194:195], v0 offset:288
	ds_read_b64 v[196:197], v0 offset:320
	ds_read_b64 v[198:199], v0 offset:352
	ds_read_b64 v[200:201], v1 offset:512
	ds_read_b64 v[202:203], v1 offset:544
	ds_read_b64 v[204:205], v182 offset:768
	ds_read_b64 v[206:207], v182 offset:800
	ds_read_b64_tr_b16 v[210:211], v176 offset:13056
	ds_read_b64_tr_b16 v[212:213], v177 offset:17408
	ds_read_b64_tr_b16 v[214:215], v177 offset:21760
	ds_read_b64_tr_b16 v[208:209], v176 offset:8704
	ds_read_b64_tr_b16 v[216:217], v176 offset:8736
	ds_read_b64_tr_b16 v[220:221], v176 offset:8768
	ds_read_b64_tr_b16 v[222:223], v176 offset:13120
	ds_read_b64_tr_b16 v[218:219], v176 offset:13088
	ds_read_b64_tr_b16 v[230:231], v176 offset:8928
	s_waitcnt lgkmcnt(7)
	v_lshlrev_b32_e32 v232, 16, v212
	v_and_b32_e32 v233, 0xffff0000, v212
	v_lshlrev_b32_e32 v234, 16, v213
	v_and_b32_e32 v235, 0xffff0000, v213
	s_waitcnt lgkmcnt(6)
	v_lshlrev_b32_e32 v246, 16, v214
	v_and_b32_e32 v247, 0xffff0000, v214
	v_lshlrev_b32_e32 v248, 16, v215
	v_and_b32_e32 v249, 0xffff0000, v215
	v_mov_b32_e32 v159, v158
	v_mfma_f32_16x16x32_bf16 v[226:229], v[60:63], v[192:195], 0
	v_mul_f32_e64 v232, v150, v232
	v_mul_f32_e64 v233, v151, v233
	v_pk_mul_f32 v[234:235], v[152:153], v[234:235]
	v_pk_mul_f32 v[44:45], v[164:165], v[44:45]
	v_mfma_f32_16x16x32_bf16 v[60:63], v[60:63], v[188:191], 0
	v_mul_f32_e64 v46, v158, v46
	v_mul_f32_e64 v47, v159, v47
	v_pk_mul_f32 v[40:41], v[164:165], v[40:41]
	v_pk_mul_f32 v[42:43], v[158:159], v[42:43]
	v_mfma_f32_16x16x32_bf16 v[188:191], v[200:203], v[188:191], 0
	v_cvt_pk_bf16_f32 v52, v36, v37
	v_cvt_pk_bf16_f32 v53, v38, v39
	v_cvt_pk_bf16_f32 v54, v32, v33
	v_mfma_f32_16x16x32_bf16 v[200:203], v[200:203], v[192:195], 0
	v_cvt_pk_bf16_f32 v55, v34, v35
	v_cvt_pk_bf16_f32 v56, v28, v29
	v_cvt_pk_bf16_f32 v57, v30, v31
	v_mfma_f32_16x16x32_bf16 v[192:195], v[204:207], v[192:195], 0
	v_mul_f32_e64 v206, v154, v246
	v_mul_f32_e64 v207, v155, v247
	v_pk_mul_f32 v[246:247], v[156:157], v[248:249]
	v_cvt_pk_bf16_f32 v204, v232, v233
	v_cvt_pk_bf16_f32 v205, v234, v235
	v_cvt_pk_bf16_f32 v206, v206, v207
	v_cvt_pk_bf16_f32 v207, v246, v247
	v_pk_mul_f32 v[36:37], v[164:165], v[36:37]
	v_pk_mul_f32 v[32:33], v[164:165], v[32:33]
	s_waitcnt lgkmcnt(5)
	v_mfma_f32_16x16x32_bf16 v[44:47], v[208:211], v[204:207], v[44:47]
	ds_read_b64_tr_b16 v[210:211], v176 offset:13152
	ds_read_b64_tr_b16 v[208:209], v176 offset:8800
	ds_read_b64_tr_b16 v[232:233], v176 offset:8832
	v_pk_mul_f32 v[28:29], v[164:165], v[28:29]
	v_pk_mul_f32 v[38:39], v[158:159], v[38:39]
	s_waitcnt lgkmcnt(4)
	v_mfma_f32_16x16x32_bf16 v[40:43], v[216:219], v[204:207], v[40:43]
	ds_read_b64_tr_b16 v[216:217], v176 offset:8864
	ds_read_b64_tr_b16 v[234:235], v176 offset:13184
	ds_read_b64_tr_b16 v[218:219], v176 offset:13216
	v_pk_mul_f32 v[34:35], v[158:159], v[34:35]
	v_pk_mul_f32 v[30:31], v[158:159], v[30:31]
	v_mfma_f32_16x16x32_bf16 v[36:39], v[220:223], v[204:207], v[36:39]
	v_ashrrev_i32_e32 v245, 31, v244
	v_ashrrev_i32_e32 v237, 31, v236
	v_cvt_pk_bf16_f32 v58, v24, v25
	s_waitcnt lgkmcnt(4)
	v_mfma_f32_16x16x32_bf16 v[32:35], v[208:211], v[204:207], v[32:35]
	ds_read_b64_tr_b16 v[208:209], v176 offset:8896
	ds_read_b64_tr_b16 v[210:211], v176 offset:13248
	v_cvt_pk_bf16_f32 v59, v26, v27
	s_waitcnt lgkmcnt(3)
	v_mfma_f32_16x16x32_bf16 v[220:223], v[232:235], v[204:207], v[28:31]
	ds_read_b64_tr_b16 v[232:233], v176 offset:13280
	v_cvt_pk_bf16_f32 v48, v20, v21
	v_cvt_pk_bf16_f32 v49, v22, v23
	v_lshlrev_b64 v[28:29], 13, v[244:245]
	v_cvt_pk_bf16_f32 v50, v16, v17
	v_cvt_pk_bf16_f32 v51, v18, v19
	v_pk_mul_f32 v[24:25], v[164:165], v[24:25]
	v_pk_mul_f32 v[20:21], v[164:165], v[20:21]
	v_pk_mul_f32 v[16:17], v[164:165], v[16:17]
	v_pk_mul_f32 v[26:27], v[158:159], v[26:27]
	v_pk_mul_f32 v[22:23], v[158:159], v[22:23]
	v_pk_mul_f32 v[18:19], v[158:159], v[18:19]
	v_ashrrev_i32_e32 v239, 31, v238
	v_ashrrev_i32_e32 v241, 31, v240
	v_lshlrev_b64 v[236:237], 11, v[236:237]
	v_or_b32_e32 v28, v28, v181
	v_lshlrev_b64 v[246:247], 11, v[238:239]
	v_lshlrev_b64 v[248:249], 11, v[240:241]
	s_waitcnt lgkmcnt(3)
	v_mfma_f32_16x16x32_bf16 v[216:219], v[216:219], v[204:207], v[24:27]
	v_lshl_add_u64 v[234:235], v[170:171], 0, v[236:237]
	v_lshl_add_u64 v[236:237], s[36:37], 0, v[28:29]
	v_lshl_add_u64 v[238:239], s[38:39], 0, v[28:29]
	s_waitcnt lgkmcnt(1)
	v_mfma_f32_16x16x32_bf16 v[208:211], v[208:211], v[204:207], v[20:23]
	ds_read_b64 v[24:25], v1 offset:576
	ds_read_b64 v[26:27], v1 offset:608
	v_lshl_add_u64 v[240:241], s[40:41], 0, v[28:29]
	ds_read_b64 v[28:29], v182 offset:832
	ds_read_b64 v[30:31], v182 offset:864
	s_waitcnt lgkmcnt(4)
	v_mfma_f32_16x16x32_bf16 v[204:207], v[230:233], v[204:207], v[16:19]
	v_mov_b32_e32 v3, v2
	v_add_u32_e32 v183, 0x6000, v178
	v_add_u32_e32 v184, 0x7000, v178
	ds_read_b64 v[16:17], v178 offset:64
	ds_read_b64 v[18:19], v178 offset:96
	v_mfma_f32_16x16x32_bf16 v[226:229], v[52:55], v[196:199], v[226:229]
	v_add_u32_e32 v185, 0x8800, v179
	v_add_u32_e32 v186, 0x9800, v179
	s_add_i32 s57, s57, 2
	s_waitcnt lgkmcnt(0)
	v_mfma_f32_16x16x32_bf16 v[20:23], v[52:55], v[16:19], v[60:63]
	ds_read_b64 v[52:53], v0 offset:384
	ds_read_b64 v[54:55], v0 offset:416
	s_nop 1
	ds_read_b64 v[60:61], v178 offset:128
	ds_read_b64 v[62:63], v178 offset:160
	v_add_u32_e32 v173, 64, v173
	v_subrev_u32_e32 v180, 64, v180
	v_mfma_f32_16x16x32_bf16 v[16:19], v[24:27], v[16:19], v[188:191]
	s_cmp_ge_u32 s1, s58
	v_mfma_f32_16x16x32_bf16 v[24:27], v[24:27], v[196:199], v[200:203]
	v_mfma_f32_16x16x32_bf16 v[28:31], v[28:31], v[196:199], v[192:195]
	s_nop 2
	ds_read_b64 v[192:193], v1 offset:640
	ds_read_b64 v[194:195], v1 offset:672
	ds_read_b64 v[196:197], v178 offset:192
	ds_read_b64 v[198:199], v178 offset:224
	ds_read_b64 v[200:201], v0 offset:448
	ds_read_b64 v[202:203], v0 offset:480
	s_waitcnt lgkmcnt(8)
	v_mfma_f32_16x16x32_bf16 v[188:191], v[56:59], v[52:55], v[226:229]
	s_waitcnt lgkmcnt(6)
	v_mfma_f32_16x16x32_bf16 v[20:23], v[56:59], v[60:63], v[20:23]
	ds_read_b64 v[56:57], v182 offset:896
	ds_read_b64 v[58:59], v182 offset:928
	ds_read_b64 v[226:227], v1 offset:704
	ds_read_b64 v[228:229], v1 offset:736
	ds_read_b64 v[230:231], v182 offset:960
	ds_read_b64 v[232:233], v182 offset:992
	s_waitcnt vmcnt(5)
	ds_write_b128 v175, v[12:15] offset:26112
	ds_write_b128 v175, v[8:11] offset:34816
	ds_write_b128 v175, v[4:7] offset:43520
	s_waitcnt lgkmcnt(13)
	v_mfma_f32_16x16x32_bf16 v[16:19], v[192:195], v[60:63], v[16:19]
	v_mfma_f32_16x16x32_bf16 v[4:7], v[192:195], v[52:55], v[24:27]
	s_waitcnt lgkmcnt(7)
	v_mfma_f32_16x16x32_bf16 v[8:11], v[56:59], v[52:55], v[28:31]
	s_nop 0
	v_cvt_pk_bf16_f32 v24, v44, v45
	v_cvt_pk_bf16_f32 v25, v46, v47
	v_cvt_pk_bf16_f32 v26, v40, v41
	s_waitcnt lgkmcnt(5)
	v_mfma_f32_16x16x32_bf16 v[16:19], v[226:229], v[196:199], v[16:19]
	v_mul_f32_e64 v28, v164, v44
	v_mul_f32_e64 v29, v165, v45
	v_cvt_pk_bf16_f32 v27, v42, v43
	v_pk_mul_f32 v[30:31], v[158:159], v[46:47]
	v_mfma_f32_16x16x32_bf16 v[4:7], v[226:229], v[200:203], v[4:7]
	v_cvt_pk_bf16_f32 v52, v36, v37
	s_nop 1
	v_pk_mul_f32 v[18:19], v[146:147], v[18:19]
	v_pk_mul_f32 v[0:1], v[142:143], v[16:17]
	s_waitcnt lgkmcnt(3)
	v_mfma_f32_16x16x32_bf16 v[8:11], v[230:233], v[200:203], v[8:11]
	v_cvt_pk_bf16_f32 v0, v0, v1
	v_pk_mul_f32 v[6:7], v[148:149], v[6:7]
	v_pk_mul_f32 v[4:5], v[144:145], v[4:5]
	v_cvt_pk_bf16_f32 v1, v18, v19
	v_cvt_pk_bf16_f32 v4, v4, v5
	s_nop 2
	v_pk_mul_f32 v[16:17], v[146:147], v[10:11]
	v_pk_mul_f32 v[44:45], v[142:143], v[8:9]
	v_cvt_pk_bf16_f32 v5, v6, v7
	v_cvt_pk_bf16_f32 v6, v44, v45
	v_cvt_pk_bf16_f32 v7, v16, v17
	v_mfma_f32_16x16x32_bf16 v[12:15], v[48:51], v[200:203], v[188:191]
	v_cvt_pk_bf16_f32 v53, v38, v39
	v_pk_mul_f32 v[38:39], v[158:159], v[38:39]
	v_pk_mul_f32 v[36:37], v[164:165], v[36:37]
	v_mfma_f32_16x16x32_bf16 v[20:23], v[48:51], v[196:199], v[20:23]
	v_cvt_pk_bf16_f32 v54, v32, v33
	v_cvt_pk_bf16_f32 v55, v34, v35
	v_pk_mul_f32 v[42:43], v[158:159], v[42:43]
	v_mfma_f32_16x16x32_bf16 v[8:11], v[212:215], v[0:3], 0
	v_mul_f32_e64 v40, v164, v40
	v_mul_f32_e64 v41, v165, v41
	v_pk_mul_f32 v[34:35], v[158:159], v[34:35]
	v_pk_mul_f32 v[32:33], v[164:165], v[32:33]
	v_mfma_f32_16x16x32_bf16 v[4:7], v[212:215], v[4:7], 0
	v_mul_f32_e64 v50, v158, v222
	v_mul_f32_e64 v51, v159, v223
	s_nop 0
	v_pk_fma_f32 v[8:9], v[162:163], v[20:21], v[8:9]
	v_pk_mul_f32 v[48:49], v[164:165], v[220:221]
	v_cvt_pk_bf16_f32 v8, v8, v9
	v_cvt_pk_bf16_f32 v56, v220, v221
	s_nop 0
	v_pk_fma_f32 v[0:1], v[166:167], v[14:15], v[6:7]
	v_pk_fma_f32 v[6:7], v[168:169], v[22:23], v[10:11]
	v_pk_fma_f32 v[4:5], v[160:161], v[12:13], v[4:5]
	v_cvt_pk_bf16_f32 v9, v6, v7
	v_cvt_pk_bf16_f32 v4, v4, v5
	v_cvt_pk_bf16_f32 v5, v0, v1
	global_store_dwordx2 v[242:243], v[8:9], off
	global_store_dwordx2 v[234:235], v[4:5], off
	global_load_dwordx4 v[12:15], v[236:237], off
	s_nop 0
	global_load_dwordx4 v[8:11], v[238:239], off
	global_load_dwordx4 v[4:7], v[240:241], off
	s_waitcnt lgkmcnt(0)
	s_barrier
	s_cselect_b32 s99, 1, 0
	s_cmp_eq_u32 s98, 0
	s_cbranch_scc1 .Lstg_skip2
	s_sleep 3
.Lstg_skip2:
	s_cmp_lg_u32 s99, 0
	ds_read_b64 v[16:17], v183 offset:1536
	ds_read_b64 v[18:19], v183 offset:1568
	ds_read_b64 v[20:21], v184 offset:1792
	ds_read_b64 v[22:23], v184 offset:1824
	ds_read_b64 v[60:61], v184 offset:1856
	ds_read_b64 v[62:63], v184 offset:1888
	ds_read_b64 v[44:45], v185
	ds_read_b64 v[46:47], v185 offset:32
	ds_read_b64 v[188:189], v186 offset:256
	ds_read_b64 v[190:191], v186 offset:288
	ds_read_b64_tr_b16 v[194:195], v176 offset:39168
	ds_read_b64_tr_b16 v[196:197], v177 offset:43520
	ds_read_b64_tr_b16 v[198:199], v177 offset:47872
	ds_read_b64_tr_b16 v[192:193], v176 offset:34816
	ds_read_b64_tr_b16 v[200:201], v176 offset:34848
	ds_read_b64_tr_b16 v[212:213], v176 offset:34880
	ds_read_b64_tr_b16 v[214:215], v176 offset:39232
	s_waitcnt lgkmcnt(13)
	v_mfma_f32_16x16x32_bf16 v[226:229], v[24:27], v[20:23], 0
	s_waitcnt lgkmcnt(5)
	v_lshlrev_b32_e32 v0, 16, v196
	v_and_b32_e32 v1, 0xffff0000, v196
	v_pk_mul_f32 v[0:1], v[150:151], v[0:1]
	v_mfma_f32_16x16x32_bf16 v[234:237], v[24:27], v[16:19], 0
	v_lshlrev_b32_e32 v24, 16, v197
	v_and_b32_e32 v25, 0xffff0000, v197
	v_pk_mul_f32 v[24:25], v[152:153], v[24:25]
	v_mfma_f32_16x16x32_bf16 v[238:241], v[44:47], v[16:19], 0
	s_waitcnt lgkmcnt(4)
	v_lshlrev_b32_e32 v16, 16, v198
	v_and_b32_e32 v17, 0xffff0000, v198
	v_lshlrev_b32_e32 v18, 16, v199
	v_and_b32_e32 v19, 0xffff0000, v199
	v_mfma_f32_16x16x32_bf16 v[242:245], v[44:47], v[20:23], 0
	ds_read_b64_tr_b16 v[202:203], v176 offset:39200
	ds_read_b64_tr_b16 v[230:231], v176 offset:35040
	v_cvt_pk_bf16_f32 v57, v222, v223
	v_cvt_pk_bf16_f32 v58, v216, v217
	v_mfma_f32_16x16x32_bf16 v[188:191], v[188:191], v[20:23], 0
	v_mul_f32_e64 v20, v154, v16
	v_mul_f32_e64 v21, v155, v17
	v_pk_mul_f32 v[22:23], v[156:157], v[18:19]
	v_cvt_pk_bf16_f32 v16, v0, v1
	v_cvt_pk_bf16_f32 v17, v24, v25
	v_cvt_pk_bf16_f32 v18, v20, v21
	v_cvt_pk_bf16_f32 v19, v22, v23
	ds_read_b64_tr_b16 v[22:23], v176 offset:39264
	ds_read_b64_tr_b16 v[20:21], v176 offset:34912
	ds_read_b64_tr_b16 v[24:25], v176 offset:34944
	s_waitcnt lgkmcnt(8)
	v_mfma_f32_16x16x32_bf16 v[44:47], v[192:195], v[16:19], v[28:31]
	ds_read_b64_tr_b16 v[192:193], v176 offset:34976
	ds_read_b64_tr_b16 v[26:27], v176 offset:39296
	ds_read_b64_tr_b16 v[194:195], v176 offset:39328
	ds_read_b64_tr_b16 v[232:233], v176 offset:39392
	v_cvt_pk_bf16_f32 v59, v218, v219
	s_waitcnt lgkmcnt(9)
	v_mfma_f32_16x16x32_bf16 v[36:39], v[212:215], v[16:19], v[36:39]
	ds_read_b64_tr_b16 v[212:213], v176 offset:35008
	ds_read_b64_tr_b16 v[214:215], v176 offset:39360
	s_waitcnt lgkmcnt(10)
	v_mfma_f32_16x16x32_bf16 v[40:43], v[200:203], v[16:19], v[40:43]
	v_mul_f32_e64 v202, v158, v218
	v_mul_f32_e64 v203, v159, v219
	v_pk_mul_f32 v[200:201], v[164:165], v[216:217]
	ds_read_b64 v[216:217], v183 offset:1664
	ds_read_b64 v[218:219], v183 offset:1696
	s_waitcnt lgkmcnt(9)
	v_mfma_f32_16x16x32_bf16 v[32:35], v[20:23], v[16:19], v[32:35]
	v_mul_f32_e64 v22, v158, v210
	v_mul_f32_e64 v23, v159, v211
	v_pk_mul_f32 v[20:21], v[164:165], v[208:209]
	s_waitcnt lgkmcnt(6)
	v_mfma_f32_16x16x32_bf16 v[28:31], v[24:27], v[16:19], v[48:51]
	s_waitcnt lgkmcnt(5)
	v_mfma_f32_16x16x32_bf16 v[24:27], v[192:195], v[16:19], v[200:203]
	ds_read_b64 v[192:193], v185 offset:64
	ds_read_b64 v[194:195], v185 offset:96
	v_pk_mul_f32 v[50:51], v[158:159], v[206:207]
	v_pk_mul_f32 v[48:49], v[164:165], v[204:205]
	s_waitcnt lgkmcnt(4)
	v_mfma_f32_16x16x32_bf16 v[20:23], v[212:215], v[16:19], v[20:23]
	ds_read_b64 v[212:213], v186 offset:320
	ds_read_b64 v[214:215], v186 offset:352
	v_cvt_pk_bf16_f32 v202, v204, v205
	v_cvt_pk_bf16_f32 v203, v206, v207
	v_mfma_f32_16x16x32_bf16 v[16:19], v[230:233], v[16:19], v[48:51]
	ds_read_b64 v[204:205], v183 offset:1728
	ds_read_b64 v[206:207], v183 offset:1760
	v_cvt_pk_bf16_f32 v200, v208, v209
	v_cvt_pk_bf16_f32 v201, v210, v211
	ds_read_b64 v[48:49], v183 offset:1600
	ds_read_b64 v[50:51], v183 offset:1632
	v_mfma_f32_16x16x32_bf16 v[226:229], v[52:55], v[60:63], v[226:229]
	s_waitcnt lgkmcnt(0)
	v_mfma_f32_16x16x32_bf16 v[52:55], v[52:55], v[48:51], v[234:237]
	v_mfma_f32_16x16x32_bf16 v[48:51], v[192:195], v[48:51], v[238:241]
	v_mfma_f32_16x16x32_bf16 v[192:195], v[192:195], v[60:63], v[242:245]
	v_mfma_f32_16x16x32_bf16 v[60:63], v[212:215], v[60:63], v[188:191]
	s_nop 2
	ds_read_b64 v[188:189], v184 offset:1920
	ds_read_b64 v[190:191], v184 offset:1952
	s_waitcnt lgkmcnt(0)
	v_mfma_f32_16x16x32_bf16 v[212:215], v[56:59], v[188:191], v[226:229]
	v_mfma_f32_16x16x32_bf16 v[52:55], v[56:59], v[216:219], v[52:55]
	ds_read_b64 v[56:57], v185 offset:128
	ds_read_b64 v[58:59], v185 offset:160
	s_waitcnt lgkmcnt(0)
	v_mfma_f32_16x16x32_bf16 v[48:51], v[56:59], v[216:219], v[48:51]
	v_mfma_f32_16x16x32_bf16 v[56:59], v[56:59], v[188:191], v[192:195]
	s_nop 2
	ds_read_b64 v[192:193], v186 offset:384
	ds_read_b64 v[194:195], v186 offset:416
	s_waitcnt lgkmcnt(0)
	v_mfma_f32_16x16x32_bf16 v[60:63], v[192:195], v[188:191], v[60:63]
	ds_read_b64 v[188:189], v184 offset:1984
	ds_read_b64 v[190:191], v184 offset:2016
	ds_read_b64 v[182:183], v185 offset:192
	ds_read_b64 v[184:185], v185 offset:224
	s_waitcnt lgkmcnt(0)
	v_mfma_f32_16x16x32_bf16 v[48:51], v[182:185], v[204:207], v[48:51]
	s_nop 7
	v_pk_mul_f32 v[50:51], v[146:147], v[50:51]
	v_mfma_f32_16x16x32_bf16 v[56:59], v[182:185], v[188:191], v[56:59]
	ds_read_b64 v[182:183], v186 offset:448
	ds_read_b64 v[184:185], v186 offset:480
	v_pk_mul_f32 v[0:1], v[142:143], v[48:49]
	s_waitcnt lgkmcnt(0)
	v_mfma_f32_16x16x32_bf16 v[60:63], v[182:185], v[188:191], v[60:63]
	s_nop 3
	v_mul_f32_e64 v182, v148, v58
	v_mul_f32_e64 v183, v149, v59
	v_pk_mul_f32 v[48:49], v[144:145], v[56:57]
	v_cvt_pk_bf16_f32 v0, v0, v1
	v_pk_mul_f32 v[62:63], v[146:147], v[62:63]
	v_pk_mul_f32 v[60:61], v[142:143], v[60:61]
	v_cvt_pk_bf16_f32 v1, v50, v51
	v_cvt_pk_bf16_f32 v48, v48, v49
	v_cvt_pk_bf16_f32 v49, v182, v183
	v_cvt_pk_bf16_f32 v50, v60, v61
	v_cvt_pk_bf16_f32 v51, v62, v63
	v_mfma_f32_16x16x32_bf16 v[192:195], v[200:203], v[188:191], v[212:215]
	v_mfma_f32_16x16x32_bf16 v[52:55], v[200:203], v[204:207], v[52:55]
	v_lshl_add_u64 v[200:201], v[170:171], 0, v[246:247]
	v_lshl_add_u64 v[202:203], v[170:171], 0, v[248:249]
	v_mfma_f32_16x16x32_bf16 v[56:59], v[196:199], v[0:3], 0
	v_mfma_f32_16x16x32_bf16 v[48:51], v[196:199], v[48:51], 0
	s_nop 6
	v_fma_f32 v52, v162, v52, v56
	v_fma_f32 v53, v163, v53, v57
	v_pk_fma_f32 v[0:1], v[166:167], v[194:195], v[50:51]
	v_pk_fma_f32 v[50:51], v[168:169], v[54:55], v[58:59]
	v_pk_fma_f32 v[48:49], v[160:161], v[192:193], v[48:49]
	v_cvt_pk_bf16_f32 v52, v52, v53
	v_cvt_pk_bf16_f32 v53, v50, v51
	v_cvt_pk_bf16_f32 v48, v48, v49
	v_cvt_pk_bf16_f32 v49, v0, v1
	global_store_dwordx2 v[200:201], v[52:53], off
	global_store_dwordx2 v[202:203], v[48:49], off
	s_cbranch_scc0 .LBB0_1370
	s_andn2_b64 vcc, exec, s[6:7]
	s_cbranch_vccnz .LBB0_1354
	s_add_u32 s0, s28, s14
	s_addc_u32 s1, s29, s15
	v_lshl_add_u64 v[0:1], v[112:113], 2, s[0:1]
	s_waitcnt vmcnt(2)
	v_lshl_add_u64 v[4:5], v[0:1], 0, v[76:77]
	global_store_dword v[4:5], v44, off nt
	v_lshl_add_u64 v[4:5], v[0:1], 0, v[78:79]
	global_store_dword v[4:5], v45, off nt
	v_lshl_add_u64 v[4:5], v[0:1], 0, v[80:81]
	global_store_dword v[4:5], v46, off nt
	v_lshl_add_u64 v[4:5], v[0:1], 0, v[82:83]
	global_store_dword v[4:5], v47, off nt
	v_lshl_add_u64 v[4:5], v[0:1], 0, v[84:85]
	global_store_dword v[4:5], v40, off nt
	v_lshl_add_u64 v[4:5], v[0:1], 0, v[86:87]
	global_store_dword v[4:5], v41, off nt
	v_lshl_add_u64 v[4:5], v[0:1], 0, v[88:89]
	global_store_dword v[4:5], v42, off nt
	v_lshl_add_u64 v[4:5], v[0:1], 0, v[90:91]
	global_store_dword v[4:5], v43, off nt
	v_lshl_add_u64 v[4:5], v[0:1], 0, v[92:93]
	global_store_dword v[4:5], v36, off nt
	v_lshl_add_u64 v[4:5], v[0:1], 0, v[94:95]
	global_store_dword v[4:5], v37, off nt
	v_lshl_add_u64 v[4:5], v[0:1], 0, v[96:97]
	global_store_dword v[4:5], v38, off nt
	v_lshl_add_u64 v[4:5], v[0:1], 0, v[98:99]
	global_store_dword v[4:5], v39, off nt
	v_lshl_add_u64 v[4:5], v[0:1], 0, v[100:101]
	global_store_dword v[4:5], v32, off nt
	v_lshl_add_u64 v[4:5], v[0:1], 0, v[102:103]
	global_store_dword v[4:5], v33, off nt
	v_lshl_add_u64 v[4:5], v[0:1], 0, v[104:105]
	global_store_dword v[4:5], v34, off nt
	v_lshl_add_u64 v[4:5], v[0:1], 0, v[106:107]
	global_store_dword v[4:5], v35, off nt
	v_lshl_add_u64 v[4:5], v[0:1], 0, v[108:109]
	global_store_dword v[4:5], v28, off nt
	v_lshl_add_u64 v[4:5], v[0:1], 0, v[110:111]
	global_store_dword v[4:5], v29, off nt
	v_lshl_add_u64 v[4:5], v[0:1], 0, v[138:139]
	global_store_dword v[4:5], v30, off nt
	v_lshl_add_u64 v[4:5], v[0:1], 0, v[136:137]
	global_store_dword v[4:5], v31, off nt
	v_lshl_add_u64 v[4:5], v[0:1], 0, v[134:135]
	global_store_dword v[4:5], v24, off nt
	v_lshl_add_u64 v[4:5], v[0:1], 0, v[132:133]
	global_store_dword v[4:5], v25, off nt
	v_lshl_add_u64 v[4:5], v[0:1], 0, v[130:131]
	global_store_dword v[4:5], v26, off nt
	v_lshl_add_u64 v[4:5], v[0:1], 0, v[128:129]
	global_store_dword v[4:5], v27, off nt
	v_lshl_add_u64 v[4:5], v[0:1], 0, v[126:127]
	global_store_dword v[4:5], v20, off nt
	v_lshl_add_u64 v[4:5], v[0:1], 0, v[124:125]
	global_store_dword v[4:5], v21, off nt
	v_lshl_add_u64 v[4:5], v[0:1], 0, v[122:123]
	global_store_dword v[4:5], v22, off nt
	v_lshl_add_u64 v[4:5], v[0:1], 0, v[120:121]
	global_store_dword v[4:5], v23, off nt
	v_lshl_add_u64 v[4:5], v[0:1], 0, v[118:119]
	global_store_dword v[4:5], v16, off nt
	v_lshl_add_u64 v[4:5], v[0:1], 0, v[116:117]
	global_store_dword v[4:5], v17, off nt
	v_lshl_add_u64 v[4:5], v[0:1], 0, v[114:115]
	v_lshl_add_u64 v[0:1], v[0:1], 0, v[140:141]
	global_store_dword v[4:5], v18, off nt
	global_store_dword v[0:1], v19, off nt
	s_branch .LBB0_1354
